# attention epilogue: the 32 LDS exchange reads issued as one batch (were one round trip each)
# baseline (speedup 1.0000x reference)
; __device__ __forceinline__ void attn_unit(LAS unsigned char* lds, const bf16_t* Qb, const bf16_t* Kb, const bf16_t* Vb, bf16_t* mix,
;                                           int b, int head, int qbase  , float lam, float post_scale, const float* subg) {
;     ...
;     asm volatile("s_waitcnt lgkmcnt(0)" ::: "memory");
;     __builtin_amdgcn_s_barrier();
;     asm volatile("" ::: "memory");
;     if (c == 0) {
;         const float i0 = 1.f / lt;
;         float ss = 0.f;
; #pragma unroll
;         for (int d = 0; d < 4; ++d)
; #pragma unroll
;             for (int i = 0; i < 16; ++i) { const float o = O[d][i] * i0 - X[(d * 16 + i) * 64]; O[d][i] = o; ss += o * o; }
;         ss += __shfl_xor(ss, 32);
;         const float rn = rsqrtf(ss * (1.f / 128.f) + EPSN) * post_scale;
;         const int qrow = qbase < CTXL ? (MLAT + b * CTXL + qidx_e) : (b * SEQ + qidx_e - CTXL);
;         bf16_t* orow = mix + (size_t)qrow * DM + head * 128;
; #pragma unroll
;         for (int d = 0; d < 4; ++d)
; #pragma unroll
;             for (int i4 = 0; i4 < 4; ++i4) {
;                 const int dv = 32 * d + 8 * i4 + 4 * h_e;
;                 const f32x4 g = *(const f32x4*)(subg + dv);
.LBB0_377:
	s_waitcnt lgkmcnt(0)
	s_barrier
	s_cmpk_gt_u32 s43, 0xff
	s_cbranch_scc1 .LBB0_337
	v_lshrrev_b32_e32 v83, 3, v222
	v_and_b32_e32 v83, 4, v83
	v_lshlrev_b32_e32 v83, 2, v83
	global_load_dwordx4 v[84:87], v83, s[10:11]
	global_load_dwordx4 v[88:91], v83, s[10:11] offset:32
	global_load_dwordx4 v[92:95], v83, s[10:11] offset:64
	global_load_dwordx4 v[96:99], v83, s[10:11] offset:96
	global_load_dwordx4 v[100:103], v83, s[10:11] offset:128
	global_load_dwordx4 v[104:107], v83, s[10:11] offset:160
	global_load_dwordx4 v[108:111], v83, s[10:11] offset:192
	global_load_dwordx4 v[112:115], v83, s[10:11] offset:224
	global_load_dwordx4 v[116:119], v83, s[10:11] offset:256
	global_load_dwordx4 v[120:123], v83, s[10:11] offset:288
	global_load_dwordx4 v[124:127], v83, s[10:11] offset:320
	global_load_dwordx4 v[128:131], v83, s[10:11] offset:352
	global_load_dwordx4 v[132:135], v83, s[10:11] offset:384
	global_load_dwordx4 v[136:139], v83, s[10:11] offset:416
	global_load_dwordx4 v[140:143], v83, s[10:11] offset:448
	global_load_dwordx4 v[144:147], v83, s[10:11] offset:480
	ds_read2st64_b32 v[148:149], v79 offset1:1
	ds_read2st64_b32 v[150:151], v79 offset0:20 offset1:21
	ds_read2st64_b32 v[152:153], v79 offset0:2 offset1:3
	ds_read2st64_b32 v[154:155], v79 offset0:4 offset1:5
	ds_read2st64_b32 v[156:157], v79 offset0:6 offset1:7
	ds_read2st64_b32 v[158:159], v79 offset0:8 offset1:9
	ds_read2st64_b32 v[160:161], v79 offset0:10 offset1:11
	ds_read2st64_b32 v[162:163], v79 offset0:12 offset1:13
	ds_read2st64_b32 v[164:165], v79 offset0:14 offset1:15
	ds_read2st64_b32 v[166:167], v79 offset0:16 offset1:17
	ds_read2st64_b32 v[170:171], v79 offset0:18 offset1:19
	ds_read2st64_b32 v[172:173], v79 offset0:22 offset1:23
	ds_read2st64_b32 v[174:175], v79 offset0:24 offset1:25
	ds_read2st64_b32 v[182:183], v79 offset0:26 offset1:27
	ds_read2st64_b32 v[184:185], v79 offset0:28 offset1:29
	ds_read2st64_b32 v[186:187], v79 offset0:30 offset1:31
	ds_read2st64_b32 v[188:189], v79 offset0:32 offset1:33
	ds_read2st64_b32 v[190:191], v79 offset0:34 offset1:35
	ds_read2st64_b32 v[192:193], v79 offset0:36 offset1:37
	ds_read2st64_b32 v[194:195], v79 offset0:38 offset1:39
	ds_read2st64_b32 v[196:197], v79 offset0:40 offset1:41
	ds_read2st64_b32 v[198:199], v79 offset0:42 offset1:43
	ds_read2st64_b32 v[200:201], v79 offset0:44 offset1:45
	ds_read2st64_b32 v[202:203], v79 offset0:46 offset1:47
	ds_read2st64_b32 v[204:205], v79 offset0:48 offset1:49
	ds_read2st64_b32 v[206:207], v79 offset0:50 offset1:51
	ds_read2st64_b32 v[208:209], v79 offset0:52 offset1:53
	ds_read2st64_b32 v[210:211], v79 offset0:54 offset1:55
	ds_read2st64_b32 v[212:213], v79 offset0:56 offset1:57
	ds_read2st64_b32 v[214:215], v79 offset0:58 offset1:59
	ds_read2st64_b32 v[216:217], v79 offset0:60 offset1:61
	ds_read2st64_b32 v[218:219], v79 offset0:62 offset1:63
	v_div_scale_f32 v65, s[14:15], v64, v64, 1.0
	v_rcp_f32_e32 v66, v65
	s_bfe_u32 s0, s41, 0x10002
	s_and_b64 s[12:13], s[12:13], exec
	s_cselect_b32 s1, 13, 8
	v_fma_f32 v68, -v65, v66, 1.0
	v_fmac_f32_e32 v66, v68, v66
	v_div_scale_f32 v68, vcc, 1.0, v64, 1.0
	v_mul_f32_e32 v69, v68, v66
	v_fma_f32 v70, -v65, v69, v68
	v_fmac_f32_e32 v69, v70, v66
	v_fma_f32 v65, -v65, v69, v68
	v_div_fmas_f32 v65, v65, v66, v69
	v_div_fixup_f32 v64, v65, v64, 1.0
	s_movk_i32 s12, 0xff00
	s_cselect_b32 s12, s12, 0x4000
	s_waitcnt lgkmcnt(0)
	v_fma_f32 v65, v48, v64, -v148
	v_fma_f32 v48, v49, v64, -v149
	v_mul_f32_e32 v80, v48, v48
	v_fmac_f32_e32 v80, v65, v65
	s_lshl_b32 s0, s0, s1
	s_add_i32 s0, s0, s12
	v_fma_f32 v49, v50, v64, -v152
	v_fma_f32 v50, v51, v64, -v153
	v_fmac_f32_e32 v80, v49, v49
	v_fmac_f32_e32 v80, v50, v50
	s_add_i32 s0, s0, s42
	v_fma_f32 v51, v52, v64, -v154
	v_fma_f32 v52, v53, v64, -v155
	v_fmac_f32_e32 v80, v51, v51
	v_fmac_f32_e32 v80, v52, v52
	v_fma_f32 v53, v54, v64, -v156
	v_fma_f32 v54, v55, v64, -v157
	v_fmac_f32_e32 v80, v53, v53
	v_fmac_f32_e32 v80, v54, v54
	v_fma_f32 v56, v56, v64, -v158
	v_fma_f32 v55, v57, v64, -v159
	v_fmac_f32_e32 v80, v56, v56
	v_fmac_f32_e32 v80, v55, v55
	v_fma_f32 v66, v58, v64, -v160
	v_fma_f32 v58, v59, v64, -v161
	v_fmac_f32_e32 v80, v66, v66
	v_fmac_f32_e32 v80, v58, v58
	v_fma_f32 v59, v60, v64, -v162
	v_fma_f32 v57, v61, v64, -v163
	v_fmac_f32_e32 v80, v59, v59
	v_fmac_f32_e32 v80, v57, v57
	v_fma_f32 v68, v62, v64, -v164
	v_fma_f32 v61, v63, v64, -v165
	v_fmac_f32_e32 v80, v68, v68
	v_fmac_f32_e32 v80, v61, v61
	v_fma_f32 v60, v32, v64, -v166
	v_fma_f32 v32, v33, v64, -v167
	v_fma_f32 v33, v37, v64, -v151
	v_fmac_f32_e32 v80, v60, v60
	v_fmac_f32_e32 v80, v32, v32
	v_fma_f32 v62, v34, v64, -v170
	v_fma_f32 v34, v35, v64, -v171
	v_fma_f32 v35, v36, v64, -v150
	v_fmac_f32_e32 v80, v62, v62
	v_fmac_f32_e32 v80, v34, v34
	v_fmac_f32_e32 v80, v35, v35
	v_fmac_f32_e32 v80, v33, v33
	v_fma_f32 v69, v38, v64, -v172
	v_fma_f32 v63, v39, v64, -v173
	v_fmac_f32_e32 v80, v69, v69
	v_fmac_f32_e32 v80, v63, v63
	v_fma_f32 v37, v40, v64, -v174
	v_fma_f32 v36, v41, v64, -v175
	v_fmac_f32_e32 v80, v37, v37
	v_fmac_f32_e32 v80, v36, v36
	v_fma_f32 v41, v42, v64, -v182
	v_fma_f32 v39, v43, v64, -v183
	v_fmac_f32_e32 v80, v41, v41
	v_fmac_f32_e32 v80, v39, v39
	v_fma_f32 v40, v44, v64, -v184
	v_fma_f32 v38, v45, v64, -v185
	v_fmac_f32_e32 v80, v40, v40
	v_fmac_f32_e32 v80, v38, v38
	v_fma_f32 v71, v46, v64, -v186
	v_fma_f32 v47, v47, v64, -v187
	v_fma_f32 v43, v16, v64, -v188
	v_fma_f32 v42, v17, v64, -v189
	v_fmac_f32_e32 v80, v71, v71
	v_fmac_f32_e32 v80, v47, v47
	v_fmac_f32_e32 v80, v43, v43
	v_fmac_f32_e32 v80, v42, v42
	v_fma_f32 v70, v18, v64, -v190
	v_fma_f32 v45, v19, v64, -v191
; __device__ __forceinline__ void attn_unit(LAS unsigned char* lds, const bf16_t* Qb, const bf16_t* Kb, const bf16_t* Vb, bf16_t* mix,
;                                           int b, int head, int qbase  , float lam, float post_scale, const float* subg) {
;     ...
;             for (int i = 0; i < 16; ++i) { const float o = O[d][i] * i0 - X[(d * 16 + i) * 64]; O[d][i] = o; ss += o * o; }
;         ss += __shfl_xor(ss, 32);
;         const float rn = rsqrtf(ss * (1.f / 128.f) + EPSN) * post_scale;
;         const int qrow = qbase < CTXL ? (MLAT + b * CTXL + qidx_e) : (b * SEQ + qidx_e - CTXL);
;         bf16_t* orow = mix + (size_t)qrow * DM + head * 128;
	v_fmac_f32_e32 v80, v70, v70
	v_fmac_f32_e32 v80, v45, v45
	v_fma_f32 v46, v20, v64, -v192
	v_fma_f32 v44, v21, v64, -v193
	v_fmac_f32_e32 v80, v46, v46
	v_fmac_f32_e32 v80, v44, v44
	v_fma_f32 v77, v22, v64, -v194
	v_fma_f32 v75, v23, v64, -v195
	v_fmac_f32_e32 v80, v77, v77
	v_fmac_f32_e32 v80, v75, v75
	v_fma_f32 v73, v24, v64, -v196
	v_fma_f32 v72, v25, v64, -v197
	v_fmac_f32_e32 v80, v73, v73
	v_fmac_f32_e32 v80, v72, v72
	v_fma_f32 v76, v26, v64, -v198
	v_fma_f32 v74, v27, v64, -v199
	v_fmac_f32_e32 v80, v76, v76
	v_fmac_f32_e32 v80, v74, v74
	v_fma_f32 v27, v28, v64, -v200
	v_fma_f32 v26, v29, v64, -v201
	v_fmac_f32_e32 v80, v27, v27
	v_fmac_f32_e32 v80, v26, v26
	v_fma_f32 v29, v30, v64, -v202
	v_fma_f32 v28, v31, v64, -v203
	v_fmac_f32_e32 v80, v29, v29
	v_fmac_f32_e32 v80, v28, v28
	v_fma_f32 v25, v0, v64, -v204
	v_fma_f32 v24, v1, v64, -v205
	v_fmac_f32_e32 v80, v25, v25
	v_fmac_f32_e32 v80, v24, v24
	v_fma_f32 v23, v2, v64, -v206
	v_fma_f32 v22, v3, v64, -v207
	v_fmac_f32_e32 v80, v23, v23
	v_fmac_f32_e32 v80, v22, v22
	v_fma_f32 v21, v4, v64, -v208
	v_fma_f32 v20, v5, v64, -v209
	v_fmac_f32_e32 v80, v21, v21
	v_fmac_f32_e32 v80, v20, v20
	v_pk_fma_f32 v[18:19], v[6:7], v[64:65], v[210:211] op_sel_hi:[1, 0, 1] neg_lo:[0, 0, 1] neg_hi:[0, 0, 1]
	s_nop 0
	v_pk_mul_f32 v[0:1], v[18:19], v[18:19]
	s_nop 0
	v_add_f32_e32 v0, v80, v0
	v_add_f32_e32 v2, v0, v1
	v_pk_fma_f32 v[16:17], v[8:9], v[64:65], v[212:213] op_sel_hi:[1, 0, 1] neg_lo:[0, 0, 1] neg_hi:[0, 0, 1]
	s_nop 0
	v_pk_mul_f32 v[0:1], v[16:17], v[16:17]
	s_nop 0
	v_add_f32_e32 v0, v2, v0
	v_add_f32_e32 v2, v0, v1
	v_pk_fma_f32 v[8:9], v[10:11], v[64:65], v[214:215] op_sel_hi:[1, 0, 1] neg_lo:[0, 0, 1] neg_hi:[0, 0, 1]
	s_nop 0
	v_pk_mul_f32 v[0:1], v[8:9], v[8:9]
	s_nop 0
	v_add_f32_e32 v0, v2, v0
	v_add_f32_e32 v2, v0, v1
	v_pk_fma_f32 v[6:7], v[12:13], v[64:65], v[216:217] op_sel_hi:[1, 0, 1] neg_lo:[0, 0, 1] neg_hi:[0, 0, 1]
	s_nop 0
	v_pk_mul_f32 v[0:1], v[6:7], v[6:7]
	s_nop 0
	v_add_f32_e32 v0, v2, v0
	v_add_f32_e32 v2, v0, v1
	v_pk_fma_f32 v[4:5], v[14:15], v[64:65], v[218:219] op_sel_hi:[1, 0, 1] neg_lo:[0, 0, 1] neg_hi:[0, 0, 1]
	s_nop 0
	v_pk_mul_f32 v[0:1], v[4:5], v[4:5]
	s_nop 0
	v_add_f32_e32 v0, v2, v0
	v_add_f32_e32 v0, v0, v1
	ds_bpermute_b32 v1, v78, v0
	s_waitcnt lgkmcnt(0)
	v_add_f32_e32 v0, v0, v1
	v_fmamk_f32 v0, v0, 0x3c000000, v224
	v_cmp_gt_f32_e32 vcc, s33, v0
	v_mul_f32_e32 v1, 0x4b800000, v0
	s_nop 0
	v_cndmask_b32_e32 v0, v0, v1, vcc
	v_rsq_f32_e32 v0, v0
	s_nop 0
	v_mul_f32_e32 v1, 0x45800000, v0
	v_cndmask_b32_e32 v0, v0, v1, vcc
	v_mul_f32_e32 v12, v169, v0
	v_and_or_b32 v0, v67, 31, s0
	v_ashrrev_i32_e32 v1, 31, v0
	v_lshlrev_b64 v[0:1], 11, v[0:1]
	s_lshl_b32 s0, s41, 8
	v_lshl_add_u64 v[0:1], s[8:9], 0, v[0:1]
	s_and_b32 s76, s0, 0x300
	v_lshl_add_u64 v[10:11], v[0:1], 0, s[76:77]
	v_lshrrev_b32_e32 v0, 3, v67
	v_and_b32_e32 v30, 4, v0
	v_lshlrev_b32_e32 v13, 2, v30
	v_mul_f32_e32 v14, v65, v12
	v_lshlrev_b32_e32 v176, 1, v30
	s_waitcnt vmcnt(0)
; __device__ __forceinline__ unsigned pkbf(float lo, float hi) { return pg8::cvt_pk_bf16(lo, hi); }
; __device__ __forceinline__ void attn_unit(LAS unsigned char* lds, const bf16_t* Qb, const bf16_t* Kb, const bf16_t* Vb, bf16_t* mix,
;                                           int b, int head, int qbase  , float lam, float post_scale, const float* subg) {
;     ...
; #pragma unroll
;         for (int d = 0; d < 4; ++d)
; #pragma unroll
;             for (int i4 = 0; i4 < 4; ++i4) {
;                 const int dv = 32 * d + 8 * i4 + 4 * h_e;
;                 const f32x4 g = *(const f32x4*)(subg + dv);
;                 u32x2 w; w.x = pkbf(O[d][4 * i4] * rn * g[0], O[d][4 * i4 + 1] * rn * g[1]); w.y = pkbf(O[d][4 * i4 + 2] * rn * g[2], O[d][4 * i4 + 3] * rn * g[3]);
;                 *(u32x2*)(orow + dv) = w;
;             }
	v_mul_f32_e32 v0, v84, v14
	v_mul_f32_e32 v14, v48, v12
	v_mul_f32_e32 v1, v85, v14
	v_cvt_pk_bf16_f32 v14, v0, v1
	v_mul_f32_e32 v0, v49, v12
	v_mul_f32_e32 v1, v50, v12
	v_mul_f32_e32 v0, v86, v0
	v_mul_f32_e32 v1, v87, v1
	v_cvt_pk_bf16_f32 v15, v0, v1
	v_lshl_add_u64 v[0:1], v[10:11], 0, v[176:177]
	flat_store_dwordx2 v[0:1], v[14:15]
	v_mul_f32_e32 v2, v51, v12
	v_mul_f32_e32 v3, v52, v12
	v_mul_f32_e32 v10, v54, v12
	v_mul_f32_e32 v2, v88, v2
	v_mul_f32_e32 v3, v89, v3
	v_cvt_pk_bf16_f32 v2, v2, v3
	v_mul_f32_e32 v3, v53, v12
	v_mul_f32_e32 v3, v90, v3
	v_mul_f32_e32 v10, v91, v10
	v_cvt_pk_bf16_f32 v3, v3, v10
	flat_store_dwordx2 v[0:1], v[2:3] offset:16
	v_mul_f32_e32 v2, v56, v12
	v_mul_f32_e32 v3, v55, v12
	v_mul_f32_e32 v10, v58, v12
	v_mul_f32_e32 v2, v92, v2
	v_mul_f32_e32 v3, v93, v3
	v_cvt_pk_bf16_f32 v2, v2, v3
	v_mul_f32_e32 v3, v66, v12
	v_mul_f32_e32 v3, v94, v3
	v_mul_f32_e32 v10, v95, v10
	v_cvt_pk_bf16_f32 v3, v3, v10
	flat_store_dwordx2 v[0:1], v[2:3] offset:32
	v_mul_f32_e32 v2, v59, v12
	v_mul_f32_e32 v3, v57, v12
	v_mul_f32_e32 v10, v61, v12
	v_mul_f32_e32 v2, v2, v96
	v_mul_f32_e32 v3, v3, v97
	v_cvt_pk_bf16_f32 v2, v2, v3
	v_mul_f32_e32 v3, v68, v12
	v_mul_f32_e32 v3, v3, v98
	v_mul_f32_e32 v10, v10, v99
	v_cvt_pk_bf16_f32 v3, v3, v10
	flat_store_dwordx2 v[0:1], v[2:3] offset:48
	v_mul_f32_e32 v2, v60, v12
	v_mul_f32_e32 v3, v32, v12
	v_mul_f32_e32 v10, v34, v12
	v_mul_f32_e32 v2, v2, v100
	v_mul_f32_e32 v3, v3, v101
	v_cvt_pk_bf16_f32 v2, v2, v3
	v_mul_f32_e32 v3, v62, v12
	v_mul_f32_e32 v3, v3, v102
	v_mul_f32_e32 v10, v10, v103
	v_cvt_pk_bf16_f32 v3, v3, v10
	flat_store_dwordx2 v[0:1], v[2:3] offset:64
	v_mul_f32_e32 v2, v35, v12
	v_mul_f32_e32 v3, v33, v12
	v_mul_f32_e32 v10, v63, v12
	v_mul_f32_e32 v2, v2, v104
	v_mul_f32_e32 v3, v3, v105
	v_cvt_pk_bf16_f32 v2, v2, v3
	v_mul_f32_e32 v3, v69, v12
	v_mul_f32_e32 v3, v3, v106
	v_mul_f32_e32 v10, v10, v107
	v_cvt_pk_bf16_f32 v3, v3, v10
	flat_store_dwordx2 v[0:1], v[2:3] offset:80
	v_mul_f32_e32 v2, v37, v12
	v_mul_f32_e32 v3, v36, v12
	v_mul_f32_e32 v10, v39, v12
	v_mul_f32_e32 v2, v2, v108
	v_mul_f32_e32 v3, v3, v109
	v_cvt_pk_bf16_f32 v2, v2, v3
	v_mul_f32_e32 v3, v41, v12
	v_mul_f32_e32 v3, v3, v110
	v_mul_f32_e32 v10, v10, v111
	v_cvt_pk_bf16_f32 v3, v3, v10
	flat_store_dwordx2 v[0:1], v[2:3] offset:96
	v_mul_f32_e32 v2, v40, v12
	v_mul_f32_e32 v3, v38, v12
	v_mul_f32_e32 v10, v47, v12
	v_mul_f32_e32 v2, v2, v112
	v_mul_f32_e32 v3, v3, v113
	v_cvt_pk_bf16_f32 v2, v2, v3
	v_mul_f32_e32 v3, v71, v12
	v_mul_f32_e32 v3, v3, v114
	v_mul_f32_e32 v10, v10, v115
	v_cvt_pk_bf16_f32 v3, v3, v10
	flat_store_dwordx2 v[0:1], v[2:3] offset:112
	v_mul_f32_e32 v2, v43, v12
	v_mul_f32_e32 v3, v42, v12
	v_mul_f32_e32 v10, v45, v12
	v_mul_f32_e32 v2, v2, v116
	v_mul_f32_e32 v3, v3, v117
	v_cvt_pk_bf16_f32 v2, v2, v3
	v_mul_f32_e32 v3, v70, v12
	v_mul_f32_e32 v3, v3, v118
	v_mul_f32_e32 v10, v10, v119
	v_cvt_pk_bf16_f32 v3, v3, v10
	flat_store_dwordx2 v[0:1], v[2:3] offset:128
	v_mul_f32_e32 v2, v46, v12
	v_mul_f32_e32 v3, v44, v12
	v_mul_f32_e32 v10, v75, v12
	v_mul_f32_e32 v2, v2, v120
	v_mul_f32_e32 v3, v3, v121
	v_cvt_pk_bf16_f32 v2, v2, v3
	v_mul_f32_e32 v3, v77, v12
	v_mul_f32_e32 v3, v3, v122
	v_mul_f32_e32 v10, v10, v123
	v_cvt_pk_bf16_f32 v3, v3, v10
	flat_store_dwordx2 v[0:1], v[2:3] offset:144
	v_mul_f32_e32 v2, v73, v12
	v_mul_f32_e32 v3, v72, v12
	v_mul_f32_e32 v10, v74, v12
	v_mul_f32_e32 v2, v2, v124
	v_mul_f32_e32 v3, v3, v125
	v_cvt_pk_bf16_f32 v2, v2, v3
	v_mul_f32_e32 v3, v76, v12
	v_mul_f32_e32 v3, v3, v126
	v_mul_f32_e32 v10, v10, v127
	v_cvt_pk_bf16_f32 v3, v3, v10
	flat_store_dwordx2 v[0:1], v[2:3] offset:160
	v_mul_f32_e32 v2, v27, v12
	v_mul_f32_e32 v3, v26, v12
	v_mul_f32_e32 v10, v28, v12
	v_mul_f32_e32 v2, v2, v128
	v_mul_f32_e32 v3, v3, v129
	v_cvt_pk_bf16_f32 v2, v2, v3
	v_mul_f32_e32 v3, v29, v12
	v_mul_f32_e32 v3, v3, v130
	v_mul_f32_e32 v10, v10, v131
	v_cvt_pk_bf16_f32 v3, v3, v10
	flat_store_dwordx2 v[0:1], v[2:3] offset:176
	v_mul_f32_e32 v2, v25, v12
	v_mul_f32_e32 v3, v24, v12
	v_mul_f32_e32 v10, v22, v12
	v_mul_f32_e32 v2, v2, v132
	v_mul_f32_e32 v3, v3, v133
	v_cvt_pk_bf16_f32 v2, v2, v3
	v_mul_f32_e32 v3, v23, v12
	v_mul_f32_e32 v3, v3, v134
	v_mul_f32_e32 v10, v10, v135
	v_cvt_pk_bf16_f32 v3, v3, v10
	flat_store_dwordx2 v[0:1], v[2:3] offset:192
	v_mul_f32_e32 v2, v21, v12
	v_mul_f32_e32 v3, v20, v12
	v_mul_f32_e32 v10, v19, v12
	v_mul_f32_e32 v2, v2, v136
	v_mul_f32_e32 v3, v3, v137
	v_cvt_pk_bf16_f32 v2, v2, v3
	v_mul_f32_e32 v3, v18, v12
	v_mul_f32_e32 v3, v3, v138
	v_mul_f32_e32 v10, v10, v139
	v_cvt_pk_bf16_f32 v3, v3, v10
	flat_store_dwordx2 v[0:1], v[2:3] offset:208
	v_mul_f32_e32 v2, v16, v12
	v_mul_f32_e32 v3, v17, v12
	v_mul_f32_e32 v2, v2, v140
	v_mul_f32_e32 v3, v3, v141
	v_cvt_pk_bf16_f32 v2, v2, v3
	v_mul_f32_e32 v3, v8, v12
	v_mul_f32_e32 v3, v3, v142
	v_mul_f32_e32 v8, v9, v12
	v_mul_f32_e32 v8, v8, v143
	v_cvt_pk_bf16_f32 v3, v3, v8
	flat_store_dwordx2 v[0:1], v[2:3] offset:224
	v_mul_f32_e32 v2, v6, v12
	v_mul_f32_e32 v3, v7, v12
	v_mul_f32_e32 v2, v2, v144
	v_mul_f32_e32 v3, v3, v145
	v_cvt_pk_bf16_f32 v2, v2, v3
	v_mul_f32_e32 v3, v4, v12
	v_mul_f32_e32 v3, v3, v146
	v_mul_f32_e32 v4, v5, v12
	v_mul_f32_e32 v4, v4, v147
	v_cvt_pk_bf16_f32 v3, v3, v4
	flat_store_dwordx2 v[0:1], v[2:3] offset:240
	s_branch .LBB0_337
